# GEMM main loops: in the four lighter load segments the wave waits for its own fragment reads before the closing barrier instead of after it
# speedup vs baseline: 1.0001x; 1.0001x over previous
.LBB0_227:
	ds_read_b128 v[140:143], v234
	ds_read_b128 v[144:147], v234 offset:1024
	ds_read_b128 v[148:151], v234 offset:2048
	ds_read_b128 v[170:173], v234 offset:3072
	ds_read_b128 v[174:177], v168
	ds_read_b128 v[178:181], v168 offset:1024
	ds_read_b128 v[182:185], v168 offset:2048
	ds_read_b128 v[186:189], v168 offset:3072
	ds_read_b128 v[190:193], v168 offset:4096
	ds_read_b128 v[206:209], v168 offset:5120
	ds_read_b128 v[210:213], v168 offset:6144
	ds_read_b128 v[214:217], v168 offset:7168
	global_load_lds_dwordx4 v136, s[20:21]
	s_add_i32 m0, s49, 0xe000
	s_nop 0
	global_load_lds_dwordx4 v138, s[20:21]
	s_waitcnt lgkmcnt(8)
	s_barrier
	s_waitcnt lgkmcnt(0)
	v_mfma_f32_16x16x32_bf16 v[124:127], v[140:143], v[174:177], v[124:127]
	v_mfma_f32_16x16x32_bf16 v[120:123], v[148:151], v[174:177], v[120:123]
	v_mfma_f32_16x16x32_bf16 v[108:111], v[140:143], v[182:185], v[108:111]
	v_mfma_f32_16x16x32_bf16 v[104:107], v[148:151], v[182:185], v[104:107]
	v_mfma_f32_16x16x32_bf16 v[92:95], v[140:143], v[190:193], v[92:95]
	v_mfma_f32_16x16x32_bf16 v[88:91], v[148:151], v[190:193], v[88:91]
	v_mfma_f32_16x16x32_bf16 v[76:79], v[140:143], v[210:213], v[76:79]
	v_mfma_f32_16x16x32_bf16 v[72:75], v[148:151], v[210:213], v[72:75]
	v_mfma_f32_16x16x32_bf16 v[124:127], v[144:147], v[178:181], v[124:127]
	v_mfma_f32_16x16x32_bf16 v[120:123], v[170:173], v[178:181], v[120:123]
	v_mfma_f32_16x16x32_bf16 v[108:111], v[144:147], v[186:189], v[108:111]
	v_mfma_f32_16x16x32_bf16 v[104:107], v[170:173], v[186:189], v[104:107]
	v_mfma_f32_16x16x32_bf16 v[92:95], v[144:147], v[206:209], v[92:95]
	v_mfma_f32_16x16x32_bf16 v[88:91], v[170:173], v[206:209], v[88:91]
	v_mfma_f32_16x16x32_bf16 v[76:79], v[144:147], v[214:217], v[76:79]
	v_mfma_f32_16x16x32_bf16 v[72:75], v[170:173], v[214:217], v[72:75]
	s_barrier
	s_add_i32 s62, 0, 0x14000
	s_add_i32 s59, s59, s48
	s_mov_b32 m0, s59
	ds_read_b128 v[218:221], v235
	ds_read_b128 v[222:225], v235 offset:1024
	ds_read_b128 v[226:229], v235 offset:2048
	ds_read_b128 v[230:233], v235 offset:3072
	global_load_lds_dwordx4 v130, s[22:23]
	s_add_i32 m0, s59, 0x2000
	s_nop 0
	global_load_lds_dwordx4 v134, s[22:23]
	s_waitcnt lgkmcnt(0)
	s_barrier
	v_mfma_f32_16x16x32_bf16 v[116:119], v[218:221], v[174:177], v[116:119]
	v_mfma_f32_16x16x32_bf16 v[112:115], v[226:229], v[174:177], v[112:115]
	v_mfma_f32_16x16x32_bf16 v[100:103], v[218:221], v[182:185], v[100:103]
	v_mfma_f32_16x16x32_bf16 v[96:99], v[226:229], v[182:185], v[96:99]
	v_mfma_f32_16x16x32_bf16 v[84:87], v[218:221], v[190:193], v[84:87]
	v_mfma_f32_16x16x32_bf16 v[80:83], v[226:229], v[190:193], v[80:83]
	v_mfma_f32_16x16x32_bf16 v[68:71], v[218:221], v[210:213], v[68:71]
	v_mfma_f32_16x16x32_bf16 v[64:67], v[226:229], v[210:213], v[64:67]
	v_mfma_f32_16x16x32_bf16 v[116:119], v[222:225], v[178:181], v[116:119]
	v_mfma_f32_16x16x32_bf16 v[112:115], v[230:233], v[178:181], v[112:115]
	v_mfma_f32_16x16x32_bf16 v[100:103], v[222:225], v[186:189], v[100:103]
	v_mfma_f32_16x16x32_bf16 v[96:99], v[230:233], v[186:189], v[96:99]
	v_mfma_f32_16x16x32_bf16 v[84:87], v[222:225], v[206:209], v[84:87]
	v_mfma_f32_16x16x32_bf16 v[80:83], v[230:233], v[206:209], v[80:83]
	v_mfma_f32_16x16x32_bf16 v[68:71], v[222:225], v[214:217], v[68:71]
	v_mfma_f32_16x16x32_bf16 v[64:67], v[230:233], v[214:217], v[64:67]
	s_barrier
	s_mov_b32 m0, s49
	s_add_u32 s98, s42, 0x80
	s_addc_u32 s99, s43, 0
	ds_read_b128 v[174:177], v168 offset:16384
	ds_read_b128 v[178:181], v168 offset:17408
	ds_read_b128 v[182:185], v168 offset:18432
	ds_read_b128 v[186:189], v168 offset:19456
	ds_read_b128 v[190:193], v168 offset:20480
	ds_read_b128 v[206:209], v168 offset:21504
	ds_read_b128 v[210:213], v168 offset:22528
	ds_read_b128 v[214:217], v168 offset:23552
	global_load_lds_dwordx4 v128, s[42:43]
	s_mov_b32 m0, s50
	s_nop 0
	global_load_lds_dwordx4 v132, s[42:43]
	s_waitcnt lgkmcnt(0)
	s_barrier
	v_mfma_f32_16x16x32_bf16 v[60:63], v[140:143], v[174:177], v[60:63]
	v_mfma_f32_16x16x32_bf16 v[56:59], v[148:151], v[174:177], v[56:59]
	v_mfma_f32_16x16x32_bf16 v[48:51], v[140:143], v[182:185], v[48:51]
	v_mfma_f32_16x16x32_bf16 v[40:43], v[148:151], v[182:185], v[40:43]
	v_mfma_f32_16x16x32_bf16 v[32:35], v[140:143], v[190:193], v[32:35]
	v_mfma_f32_16x16x32_bf16 v[24:27], v[148:151], v[190:193], v[24:27]
	v_mfma_f32_16x16x32_bf16 v[16:19], v[140:143], v[210:213], v[16:19]
	v_mfma_f32_16x16x32_bf16 v[8:11], v[148:151], v[210:213], v[8:11]
	v_mfma_f32_16x16x32_bf16 v[60:63], v[144:147], v[178:181], v[60:63]
	v_mfma_f32_16x16x32_bf16 v[56:59], v[170:173], v[178:181], v[56:59]
	v_mfma_f32_16x16x32_bf16 v[48:51], v[144:147], v[186:189], v[48:51]
	v_mfma_f32_16x16x32_bf16 v[40:43], v[170:173], v[186:189], v[40:43]
	v_mfma_f32_16x16x32_bf16 v[32:35], v[144:147], v[206:209], v[32:35]
	v_mfma_f32_16x16x32_bf16 v[24:27], v[170:173], v[206:209], v[24:27]
	v_mfma_f32_16x16x32_bf16 v[16:19], v[144:147], v[214:217], v[16:19]
	v_mfma_f32_16x16x32_bf16 v[8:11], v[170:173], v[214:217], v[8:11]
	s_barrier
	s_add_u32 s60, s22, 0x80000
	s_addc_u32 s61, s23, 0
	s_add_i32 s59, s62, s48
	s_mov_b32 m0, s59
	s_nop 0
	global_load_lds_dwordx4 v130, s[60:61]
	s_add_i32 m0, s59, 0x2000
	s_nop 0
	global_load_lds_dwordx4 v134, s[60:61]
	s_add_i32 s59, 0, 0x18000
	s_add_u32 s42, s42, 0x80000
	s_addc_u32 s43, s43, 0
	s_mov_b32 m0, s51
	s_waitcnt vmcnt(6)
	s_barrier
	v_mfma_f32_16x16x32_bf16 v[52:55], v[218:221], v[174:177], v[52:55]
	v_mfma_f32_16x16x32_bf16 v[44:47], v[226:229], v[174:177], v[44:47]
	v_mfma_f32_16x16x32_bf16 v[36:39], v[218:221], v[182:185], v[36:39]
	v_mfma_f32_16x16x32_bf16 v[28:31], v[226:229], v[182:185], v[28:31]
	v_mfma_f32_16x16x32_bf16 v[20:23], v[218:221], v[190:193], v[20:23]
	v_mfma_f32_16x16x32_bf16 v[12:15], v[226:229], v[190:193], v[12:15]
	v_mfma_f32_16x16x32_bf16 v[4:7], v[218:221], v[210:213], v[4:7]
	v_mfma_f32_16x16x32_bf16 v[0:3], v[226:229], v[210:213], v[0:3]
	v_mfma_f32_16x16x32_bf16 v[52:55], v[222:225], v[178:181], v[52:55]
	v_mfma_f32_16x16x32_bf16 v[44:47], v[230:233], v[178:181], v[44:47]
	v_mfma_f32_16x16x32_bf16 v[36:39], v[222:225], v[186:189], v[36:39]
	v_mfma_f32_16x16x32_bf16 v[28:31], v[230:233], v[186:189], v[28:31]
	v_mfma_f32_16x16x32_bf16 v[20:23], v[222:225], v[206:209], v[20:23]
	v_mfma_f32_16x16x32_bf16 v[12:15], v[230:233], v[206:209], v[12:15]
	v_mfma_f32_16x16x32_bf16 v[4:7], v[222:225], v[214:217], v[4:7]
	v_mfma_f32_16x16x32_bf16 v[0:3], v[230:233], v[214:217], v[0:3]
	s_barrier
	ds_read_b128 v[140:143], v236
	ds_read_b128 v[144:147], v236 offset:1024
	ds_read_b128 v[148:151], v236 offset:2048
	ds_read_b128 v[170:173], v236 offset:3072
	ds_read_b128 v[174:177], v168 offset:32768
	ds_read_b128 v[178:181], v168 offset:33792
	ds_read_b128 v[182:185], v168 offset:34816
	ds_read_b128 v[186:189], v168 offset:35840
	ds_read_b128 v[190:193], v168 offset:36864
	ds_read_b128 v[206:209], v168 offset:37888
	ds_read_b128 v[210:213], v168 offset:38912
	ds_read_b128 v[214:217], v168 offset:39936
	global_load_lds_dwordx4 v128, s[42:43]
	s_mov_b32 m0, s52
	s_nop 0
	global_load_lds_dwordx4 v132, s[42:43]
	s_waitcnt lgkmcnt(8)
	s_barrier
	s_waitcnt lgkmcnt(0)
	v_mfma_f32_16x16x32_bf16 v[124:127], v[140:143], v[174:177], v[124:127]
	v_mfma_f32_16x16x32_bf16 v[120:123], v[148:151], v[174:177], v[120:123]
	v_mfma_f32_16x16x32_bf16 v[108:111], v[140:143], v[182:185], v[108:111]
	v_mfma_f32_16x16x32_bf16 v[104:107], v[148:151], v[182:185], v[104:107]
	v_mfma_f32_16x16x32_bf16 v[92:95], v[140:143], v[190:193], v[92:95]
	v_mfma_f32_16x16x32_bf16 v[88:91], v[148:151], v[190:193], v[88:91]
	v_mfma_f32_16x16x32_bf16 v[76:79], v[140:143], v[210:213], v[76:79]
	v_mfma_f32_16x16x32_bf16 v[72:75], v[148:151], v[210:213], v[72:75]
	v_mfma_f32_16x16x32_bf16 v[124:127], v[144:147], v[178:181], v[124:127]
	v_mfma_f32_16x16x32_bf16 v[120:123], v[170:173], v[178:181], v[120:123]
	v_mfma_f32_16x16x32_bf16 v[108:111], v[144:147], v[186:189], v[108:111]
	v_mfma_f32_16x16x32_bf16 v[104:107], v[170:173], v[186:189], v[104:107]
	v_mfma_f32_16x16x32_bf16 v[92:95], v[144:147], v[206:209], v[92:95]
	v_mfma_f32_16x16x32_bf16 v[88:91], v[170:173], v[206:209], v[88:91]
	v_mfma_f32_16x16x32_bf16 v[76:79], v[144:147], v[214:217], v[76:79]
	v_mfma_f32_16x16x32_bf16 v[72:75], v[170:173], v[214:217], v[72:75]
	s_barrier
	s_add_i32 s42, 0, 0x1c000
	s_add_i32 s43, s59, s48
	s_add_u32 s100, s22, 0x80
	s_addc_u32 s101, s23, 0
	s_mov_b32 m0, s43
	ds_read_b128 v[218:221], v237
	ds_read_b128 v[222:225], v237 offset:1024
	ds_read_b128 v[226:229], v237 offset:2048
	ds_read_b128 v[230:233], v237 offset:3072
	global_load_lds_dwordx4 v130, s[100:101]
	s_add_i32 m0, s43, 0x2000
	s_nop 0
	global_load_lds_dwordx4 v134, s[100:101]
	s_waitcnt lgkmcnt(0)
	s_barrier
	v_mfma_f32_16x16x32_bf16 v[116:119], v[218:221], v[174:177], v[116:119]
	v_mfma_f32_16x16x32_bf16 v[112:115], v[226:229], v[174:177], v[112:115]
	v_mfma_f32_16x16x32_bf16 v[100:103], v[218:221], v[182:185], v[100:103]
	v_mfma_f32_16x16x32_bf16 v[96:99], v[226:229], v[182:185], v[96:99]
	v_mfma_f32_16x16x32_bf16 v[84:87], v[218:221], v[190:193], v[84:87]
	v_mfma_f32_16x16x32_bf16 v[80:83], v[226:229], v[190:193], v[80:83]
	v_mfma_f32_16x16x32_bf16 v[68:71], v[218:221], v[210:213], v[68:71]
	v_mfma_f32_16x16x32_bf16 v[64:67], v[226:229], v[210:213], v[64:67]
	v_mfma_f32_16x16x32_bf16 v[116:119], v[222:225], v[178:181], v[116:119]
	v_mfma_f32_16x16x32_bf16 v[112:115], v[230:233], v[178:181], v[112:115]
	v_mfma_f32_16x16x32_bf16 v[100:103], v[222:225], v[186:189], v[100:103]
	v_mfma_f32_16x16x32_bf16 v[96:99], v[230:233], v[186:189], v[96:99]
	v_mfma_f32_16x16x32_bf16 v[84:87], v[222:225], v[206:209], v[84:87]
	v_mfma_f32_16x16x32_bf16 v[80:83], v[230:233], v[206:209], v[80:83]
	v_mfma_f32_16x16x32_bf16 v[68:71], v[222:225], v[214:217], v[68:71]
	v_mfma_f32_16x16x32_bf16 v[64:67], v[230:233], v[214:217], v[64:67]
	s_barrier
	s_mov_b32 m0, s53
	ds_read_b128 v[174:177], v168 offset:49152
	ds_read_b128 v[178:181], v168 offset:50176
	ds_read_b128 v[182:185], v168 offset:51200
	ds_read_b128 v[186:189], v168 offset:52224
	ds_read_b128 v[190:193], v168 offset:53248
	ds_read_b128 v[206:209], v168 offset:54272
	ds_read_b128 v[210:213], v168 offset:55296
	ds_read_b128 v[214:217], v168 offset:56320
	global_load_lds_dwordx4 v128, s[98:99]
	s_mov_b32 m0, s54
	s_nop 0
	global_load_lds_dwordx4 v132, s[98:99]
	s_waitcnt lgkmcnt(0)
	s_barrier
	v_mfma_f32_16x16x32_bf16 v[60:63], v[140:143], v[174:177], v[60:63]
	v_mfma_f32_16x16x32_bf16 v[56:59], v[148:151], v[174:177], v[56:59]
	v_mfma_f32_16x16x32_bf16 v[48:51], v[140:143], v[182:185], v[48:51]
	v_mfma_f32_16x16x32_bf16 v[40:43], v[148:151], v[182:185], v[40:43]
	v_mfma_f32_16x16x32_bf16 v[32:35], v[140:143], v[190:193], v[32:35]
	v_mfma_f32_16x16x32_bf16 v[24:27], v[148:151], v[190:193], v[24:27]
	v_mfma_f32_16x16x32_bf16 v[16:19], v[140:143], v[210:213], v[16:19]
	v_mfma_f32_16x16x32_bf16 v[8:11], v[148:151], v[210:213], v[8:11]
	v_mfma_f32_16x16x32_bf16 v[60:63], v[144:147], v[178:181], v[60:63]
	v_mfma_f32_16x16x32_bf16 v[56:59], v[170:173], v[178:181], v[56:59]
	v_mfma_f32_16x16x32_bf16 v[48:51], v[144:147], v[186:189], v[48:51]
	v_mfma_f32_16x16x32_bf16 v[40:43], v[170:173], v[186:189], v[40:43]
	v_mfma_f32_16x16x32_bf16 v[32:35], v[144:147], v[206:209], v[32:35]
	v_mfma_f32_16x16x32_bf16 v[24:27], v[170:173], v[206:209], v[24:27]
	v_mfma_f32_16x16x32_bf16 v[16:19], v[144:147], v[214:217], v[16:19]
	v_mfma_f32_16x16x32_bf16 v[8:11], v[170:173], v[214:217], v[8:11]
	s_barrier
	s_add_u32 s22, s22, 0x80080
	s_addc_u32 s23, s23, 0
	s_add_i32 s42, s42, s48
	s_mov_b32 m0, s42
	s_nop 0
	global_load_lds_dwordx4 v130, s[22:23]
	s_add_i32 m0, s42, 0x2000
	s_nop 0
	global_load_lds_dwordx4 v134, s[22:23]
	s_add_i32 s58, s58, 2
	s_add_u32 s20, s20, 0x100
	s_addc_u32 s21, s21, 0
	s_add_u32 s35, s35, 0x100
	s_addc_u32 s57, s57, 0
	s_add_u32 s22, s20, 0xfff80080
	s_addc_u32 s23, s21, -1
	s_add_i32 s59, 0, 0x10000
	s_cmp_eq_u32 s58, 28
	s_cselect_b32 s43, s5, s23
	s_cselect_b32 s42, s6, s22
	s_cselect_b32 s23, s7, s57
	s_cselect_b32 s22, s25, s35
	s_add_i32 m0, s49, 0xc000
	s_cmp_gt_u32 s58, 29
	s_waitcnt vmcnt(6)
	s_barrier
	v_mfma_f32_16x16x32_bf16 v[52:55], v[218:221], v[174:177], v[52:55]
	v_mfma_f32_16x16x32_bf16 v[44:47], v[226:229], v[174:177], v[44:47]
	v_mfma_f32_16x16x32_bf16 v[36:39], v[218:221], v[182:185], v[36:39]
	v_mfma_f32_16x16x32_bf16 v[28:31], v[226:229], v[182:185], v[28:31]
	v_mfma_f32_16x16x32_bf16 v[20:23], v[218:221], v[190:193], v[20:23]
	v_mfma_f32_16x16x32_bf16 v[12:15], v[226:229], v[190:193], v[12:15]
	v_mfma_f32_16x16x32_bf16 v[4:7], v[218:221], v[210:213], v[4:7]
	v_mfma_f32_16x16x32_bf16 v[0:3], v[226:229], v[210:213], v[0:3]
	v_mfma_f32_16x16x32_bf16 v[52:55], v[222:225], v[178:181], v[52:55]
	v_mfma_f32_16x16x32_bf16 v[44:47], v[230:233], v[178:181], v[44:47]
	v_mfma_f32_16x16x32_bf16 v[36:39], v[222:225], v[186:189], v[36:39]
	v_mfma_f32_16x16x32_bf16 v[28:31], v[230:233], v[186:189], v[28:31]
	v_mfma_f32_16x16x32_bf16 v[20:23], v[222:225], v[206:209], v[20:23]
	v_mfma_f32_16x16x32_bf16 v[12:15], v[230:233], v[206:209], v[12:15]
	v_mfma_f32_16x16x32_bf16 v[4:7], v[222:225], v[214:217], v[4:7]
	v_mfma_f32_16x16x32_bf16 v[0:3], v[230:233], v[214:217], v[0:3]
	s_barrier
	s_cbranch_scc0 .LBB0_227
	s_cmpk_gt_u32 s14, 0xff
	s_cbranch_scc1 .Lal_e0_p
	s_barrier

.LBB0_561:
	ds_read_b128 v[72:75], v246
	ds_read_b128 v[76:79], v246 offset:1024
	ds_read_b128 v[84:87], v246 offset:2048
	ds_read_b128 v[92:95], v246 offset:3072
	ds_read_b128 v[144:147], v208
	ds_read_b128 v[148:151], v208 offset:1024
	ds_read_b128 v[188:191], v208 offset:2048
	ds_read_b128 v[210:213], v208 offset:3072
	ds_read_b128 v[214:217], v208 offset:4096
	ds_read_b128 v[218:221], v208 offset:5120
	ds_read_b128 v[222:225], v208 offset:6144
	ds_read_b128 v[226:229], v208 offset:7168
	global_load_lds_dwordx4 v184, s[22:23]
	s_add_i32 m0, s61, 0xe000
	s_nop 0
	global_load_lds_dwordx4 v186, s[22:23]
	s_waitcnt lgkmcnt(8)
	s_barrier
	s_waitcnt lgkmcnt(0)
	v_mfma_f32_16x16x32_bf16 v[140:143], v[72:75], v[144:147], v[140:143]
	v_mfma_f32_16x16x32_bf16 v[136:139], v[84:87], v[144:147], v[136:139]
	v_mfma_f32_16x16x32_bf16 v[124:127], v[72:75], v[188:191], v[124:127]
	v_mfma_f32_16x16x32_bf16 v[120:123], v[84:87], v[188:191], v[120:123]
	v_mfma_f32_16x16x32_bf16 v[108:111], v[72:75], v[214:217], v[108:111]
	v_mfma_f32_16x16x32_bf16 v[104:107], v[84:87], v[214:217], v[104:107]
	v_mfma_f32_16x16x32_bf16 v[88:91], v[72:75], v[222:225], v[88:91]
	v_mfma_f32_16x16x32_bf16 v[80:83], v[84:87], v[222:225], v[80:83]
	v_mfma_f32_16x16x32_bf16 v[140:143], v[76:79], v[148:151], v[140:143]
	v_mfma_f32_16x16x32_bf16 v[136:139], v[92:95], v[148:151], v[136:139]
	v_mfma_f32_16x16x32_bf16 v[124:127], v[76:79], v[210:213], v[124:127]
	v_mfma_f32_16x16x32_bf16 v[120:123], v[92:95], v[210:213], v[120:123]
	v_mfma_f32_16x16x32_bf16 v[108:111], v[76:79], v[218:221], v[108:111]
	v_mfma_f32_16x16x32_bf16 v[104:107], v[92:95], v[218:221], v[104:107]
	v_mfma_f32_16x16x32_bf16 v[88:91], v[76:79], v[226:229], v[88:91]
	v_mfma_f32_16x16x32_bf16 v[80:83], v[92:95], v[226:229], v[80:83]
	s_barrier
	s_add_i32 s86, 0, 0x14000
	s_add_i32 s84, s84, s60
	ds_read_b128 v[230:233], v247
	ds_read_b128 v[234:237], v247 offset:1024
	ds_read_b128 v[238:241], v247 offset:2048
	ds_read_b128 v[242:245], v247 offset:3072
	s_mov_b32 m0, s84
	s_nop 0
	global_load_lds_dwordx4 v152, s[38:39]
	s_add_i32 m0, s84, 0x2000
	s_nop 0
	global_load_lds_dwordx4 v162, s[38:39]
	s_waitcnt lgkmcnt(0)
	s_barrier
	v_mfma_f32_16x16x32_bf16 v[132:135], v[230:233], v[144:147], v[132:135]
	v_mfma_f32_16x16x32_bf16 v[128:131], v[238:241], v[144:147], v[128:131]
	v_mfma_f32_16x16x32_bf16 v[116:119], v[230:233], v[188:191], v[116:119]
	v_mfma_f32_16x16x32_bf16 v[112:115], v[238:241], v[188:191], v[112:115]
	v_mfma_f32_16x16x32_bf16 v[100:103], v[230:233], v[214:217], v[100:103]
	v_mfma_f32_16x16x32_bf16 v[96:99], v[238:241], v[214:217], v[96:99]
	v_mfma_f32_16x16x32_bf16 v[68:71], v[230:233], v[222:225], v[68:71]
	v_mfma_f32_16x16x32_bf16 v[64:67], v[238:241], v[222:225], v[64:67]
	v_mfma_f32_16x16x32_bf16 v[132:135], v[234:237], v[148:151], v[132:135]
	v_mfma_f32_16x16x32_bf16 v[128:131], v[242:245], v[148:151], v[128:131]
	v_mfma_f32_16x16x32_bf16 v[116:119], v[234:237], v[210:213], v[116:119]
	v_mfma_f32_16x16x32_bf16 v[112:115], v[242:245], v[210:213], v[112:115]
	v_mfma_f32_16x16x32_bf16 v[100:103], v[234:237], v[218:221], v[100:103]
	v_mfma_f32_16x16x32_bf16 v[96:99], v[242:245], v[218:221], v[96:99]
	v_mfma_f32_16x16x32_bf16 v[68:71], v[234:237], v[226:229], v[68:71]
	v_mfma_f32_16x16x32_bf16 v[64:67], v[242:245], v[226:229], v[64:67]
	s_barrier
	s_mov_b32 m0, s61
	s_add_u32 s98, s52, 0x80
	s_addc_u32 s99, s53, 0
	ds_read_b128 v[144:147], v208 offset:16384
	ds_read_b128 v[148:151], v208 offset:17408
	ds_read_b128 v[188:191], v208 offset:18432
	ds_read_b128 v[210:213], v208 offset:19456
	ds_read_b128 v[214:217], v208 offset:20480
	ds_read_b128 v[218:221], v208 offset:21504
	ds_read_b128 v[222:225], v208 offset:22528
	ds_read_b128 v[226:229], v208 offset:23552
	global_load_lds_dwordx4 v166, s[52:53]
	s_mov_b32 m0, s62
	s_nop 0
	global_load_lds_dwordx4 v164, s[52:53]
	s_waitcnt lgkmcnt(0)
	s_barrier
	v_mfma_f32_16x16x32_bf16 v[60:63], v[72:75], v[144:147], v[60:63]
	v_mfma_f32_16x16x32_bf16 v[56:59], v[84:87], v[144:147], v[56:59]
	v_mfma_f32_16x16x32_bf16 v[44:47], v[72:75], v[188:191], v[44:47]
	v_mfma_f32_16x16x32_bf16 v[40:43], v[84:87], v[188:191], v[40:43]
	v_mfma_f32_16x16x32_bf16 v[28:31], v[72:75], v[214:217], v[28:31]
	v_mfma_f32_16x16x32_bf16 v[24:27], v[84:87], v[214:217], v[24:27]
	v_mfma_f32_16x16x32_bf16 v[12:15], v[72:75], v[222:225], v[12:15]
	v_mfma_f32_16x16x32_bf16 v[8:11], v[84:87], v[222:225], v[8:11]
	v_mfma_f32_16x16x32_bf16 v[60:63], v[76:79], v[148:151], v[60:63]
	v_mfma_f32_16x16x32_bf16 v[56:59], v[92:95], v[148:151], v[56:59]
	v_mfma_f32_16x16x32_bf16 v[44:47], v[76:79], v[210:213], v[44:47]
	v_mfma_f32_16x16x32_bf16 v[40:43], v[92:95], v[210:213], v[40:43]
	v_mfma_f32_16x16x32_bf16 v[28:31], v[76:79], v[218:221], v[28:31]
	v_mfma_f32_16x16x32_bf16 v[24:27], v[92:95], v[218:221], v[24:27]
	v_mfma_f32_16x16x32_bf16 v[12:15], v[76:79], v[226:229], v[12:15]
	v_mfma_f32_16x16x32_bf16 v[8:11], v[92:95], v[226:229], v[8:11]
	s_barrier
	s_add_u32 s84, s38, 0x80000
	s_addc_u32 s85, s39, 0
	s_add_i32 s86, s86, s60
	s_mov_b32 m0, s86
	s_nop 0
	global_load_lds_dwordx4 v152, s[84:85]
	s_add_i32 m0, s86, 0x2000
	s_nop 0
	global_load_lds_dwordx4 v162, s[84:85]
	s_add_i32 s84, 0, 0x18000
	s_add_u32 s52, s52, 0x80000
	s_addc_u32 s53, s53, 0
	s_mov_b32 m0, s63
	s_waitcnt vmcnt(6)
	s_barrier
	v_mfma_f32_16x16x32_bf16 v[52:55], v[230:233], v[144:147], v[52:55]
	v_mfma_f32_16x16x32_bf16 v[48:51], v[238:241], v[144:147], v[48:51]
	v_mfma_f32_16x16x32_bf16 v[36:39], v[230:233], v[188:191], v[36:39]
	v_mfma_f32_16x16x32_bf16 v[32:35], v[238:241], v[188:191], v[32:35]
	v_mfma_f32_16x16x32_bf16 v[20:23], v[230:233], v[214:217], v[20:23]
	v_mfma_f32_16x16x32_bf16 v[16:19], v[238:241], v[214:217], v[16:19]
	v_mfma_f32_16x16x32_bf16 v[4:7], v[230:233], v[222:225], v[4:7]
	v_mfma_f32_16x16x32_bf16 v[0:3], v[238:241], v[222:225], v[0:3]
	v_mfma_f32_16x16x32_bf16 v[52:55], v[234:237], v[148:151], v[52:55]
	v_mfma_f32_16x16x32_bf16 v[48:51], v[242:245], v[148:151], v[48:51]
	v_mfma_f32_16x16x32_bf16 v[36:39], v[234:237], v[210:213], v[36:39]
	v_mfma_f32_16x16x32_bf16 v[32:35], v[242:245], v[210:213], v[32:35]
	v_mfma_f32_16x16x32_bf16 v[20:23], v[234:237], v[218:221], v[20:23]
	v_mfma_f32_16x16x32_bf16 v[16:19], v[242:245], v[218:221], v[16:19]
	v_mfma_f32_16x16x32_bf16 v[4:7], v[234:237], v[226:229], v[4:7]
	v_mfma_f32_16x16x32_bf16 v[0:3], v[242:245], v[226:229], v[0:3]
	s_barrier
	ds_read_b128 v[72:75], v248
	ds_read_b128 v[76:79], v248 offset:1024
	ds_read_b128 v[84:87], v248 offset:2048
	ds_read_b128 v[92:95], v248 offset:3072
	ds_read_b128 v[144:147], v208 offset:32768
	ds_read_b128 v[148:151], v208 offset:33792
	ds_read_b128 v[188:191], v208 offset:34816
	ds_read_b128 v[210:213], v208 offset:35840
	ds_read_b128 v[214:217], v208 offset:36864
	ds_read_b128 v[218:221], v208 offset:37888
	ds_read_b128 v[222:225], v208 offset:38912
	ds_read_b128 v[226:229], v208 offset:39936
	global_load_lds_dwordx4 v166, s[52:53]
	s_mov_b32 m0, s68
	s_nop 0
	global_load_lds_dwordx4 v164, s[52:53]
	s_waitcnt lgkmcnt(8)
	s_barrier
	s_waitcnt lgkmcnt(0)
	v_mfma_f32_16x16x32_bf16 v[140:143], v[72:75], v[144:147], v[140:143]
	v_mfma_f32_16x16x32_bf16 v[136:139], v[84:87], v[144:147], v[136:139]
	v_mfma_f32_16x16x32_bf16 v[124:127], v[72:75], v[188:191], v[124:127]
	v_mfma_f32_16x16x32_bf16 v[120:123], v[84:87], v[188:191], v[120:123]
	v_mfma_f32_16x16x32_bf16 v[108:111], v[72:75], v[214:217], v[108:111]
	v_mfma_f32_16x16x32_bf16 v[104:107], v[84:87], v[214:217], v[104:107]
	v_mfma_f32_16x16x32_bf16 v[88:91], v[72:75], v[222:225], v[88:91]
	v_mfma_f32_16x16x32_bf16 v[80:83], v[84:87], v[222:225], v[80:83]
	v_mfma_f32_16x16x32_bf16 v[140:143], v[76:79], v[148:151], v[140:143]
	v_mfma_f32_16x16x32_bf16 v[136:139], v[92:95], v[148:151], v[136:139]
	v_mfma_f32_16x16x32_bf16 v[124:127], v[76:79], v[210:213], v[124:127]
	v_mfma_f32_16x16x32_bf16 v[120:123], v[92:95], v[210:213], v[120:123]
	v_mfma_f32_16x16x32_bf16 v[108:111], v[76:79], v[218:221], v[108:111]
	v_mfma_f32_16x16x32_bf16 v[104:107], v[92:95], v[218:221], v[104:107]
	v_mfma_f32_16x16x32_bf16 v[88:91], v[76:79], v[226:229], v[88:91]
	v_mfma_f32_16x16x32_bf16 v[80:83], v[92:95], v[226:229], v[80:83]
	s_barrier
	s_add_i32 s52, 0, 0x1c000
	s_add_i32 s53, s84, s60
	s_add_u32 s100, s38, 0x80
	s_addc_u32 s101, s39, 0
	s_mov_b32 m0, s53
	ds_read_b128 v[230:233], v249
	ds_read_b128 v[234:237], v249 offset:1024
	ds_read_b128 v[238:241], v249 offset:2048
	ds_read_b128 v[242:245], v249 offset:3072
	global_load_lds_dwordx4 v152, s[100:101]
	s_add_i32 m0, s53, 0x2000
	s_nop 0
	global_load_lds_dwordx4 v162, s[100:101]
	s_waitcnt lgkmcnt(0)
	s_barrier
	v_mfma_f32_16x16x32_bf16 v[132:135], v[230:233], v[144:147], v[132:135]
	v_mfma_f32_16x16x32_bf16 v[128:131], v[238:241], v[144:147], v[128:131]
	v_mfma_f32_16x16x32_bf16 v[116:119], v[230:233], v[188:191], v[116:119]
	v_mfma_f32_16x16x32_bf16 v[112:115], v[238:241], v[188:191], v[112:115]
	v_mfma_f32_16x16x32_bf16 v[100:103], v[230:233], v[214:217], v[100:103]
	v_mfma_f32_16x16x32_bf16 v[96:99], v[238:241], v[214:217], v[96:99]
	v_mfma_f32_16x16x32_bf16 v[68:71], v[230:233], v[222:225], v[68:71]
	v_mfma_f32_16x16x32_bf16 v[64:67], v[238:241], v[222:225], v[64:67]
	v_mfma_f32_16x16x32_bf16 v[132:135], v[234:237], v[148:151], v[132:135]
	v_mfma_f32_16x16x32_bf16 v[128:131], v[242:245], v[148:151], v[128:131]
	v_mfma_f32_16x16x32_bf16 v[116:119], v[234:237], v[210:213], v[116:119]
	v_mfma_f32_16x16x32_bf16 v[112:115], v[242:245], v[210:213], v[112:115]
	v_mfma_f32_16x16x32_bf16 v[100:103], v[234:237], v[218:221], v[100:103]
	v_mfma_f32_16x16x32_bf16 v[96:99], v[242:245], v[218:221], v[96:99]
	v_mfma_f32_16x16x32_bf16 v[68:71], v[234:237], v[226:229], v[68:71]
	v_mfma_f32_16x16x32_bf16 v[64:67], v[242:245], v[226:229], v[64:67]
	s_barrier
	s_mov_b32 m0, s81
	ds_read_b128 v[144:147], v208 offset:49152
	ds_read_b128 v[148:151], v208 offset:50176
	ds_read_b128 v[188:191], v208 offset:51200
	ds_read_b128 v[210:213], v208 offset:52224
	ds_read_b128 v[214:217], v208 offset:53248
	ds_read_b128 v[218:221], v208 offset:54272
	ds_read_b128 v[222:225], v208 offset:55296
	ds_read_b128 v[226:229], v208 offset:56320
	global_load_lds_dwordx4 v166, s[98:99]
	s_mov_b32 m0, s82
	s_nop 0
	global_load_lds_dwordx4 v164, s[98:99]
	s_waitcnt lgkmcnt(0)
	s_barrier
	v_mfma_f32_16x16x32_bf16 v[60:63], v[72:75], v[144:147], v[60:63]
	v_mfma_f32_16x16x32_bf16 v[56:59], v[84:87], v[144:147], v[56:59]
	v_mfma_f32_16x16x32_bf16 v[44:47], v[72:75], v[188:191], v[44:47]
	v_mfma_f32_16x16x32_bf16 v[40:43], v[84:87], v[188:191], v[40:43]
	v_mfma_f32_16x16x32_bf16 v[28:31], v[72:75], v[214:217], v[28:31]
	v_mfma_f32_16x16x32_bf16 v[24:27], v[84:87], v[214:217], v[24:27]
	v_mfma_f32_16x16x32_bf16 v[12:15], v[72:75], v[222:225], v[12:15]
	v_mfma_f32_16x16x32_bf16 v[8:11], v[84:87], v[222:225], v[8:11]
	v_mfma_f32_16x16x32_bf16 v[60:63], v[76:79], v[148:151], v[60:63]
	v_mfma_f32_16x16x32_bf16 v[56:59], v[92:95], v[148:151], v[56:59]
	v_mfma_f32_16x16x32_bf16 v[44:47], v[76:79], v[210:213], v[44:47]
	v_mfma_f32_16x16x32_bf16 v[40:43], v[92:95], v[210:213], v[40:43]
	v_mfma_f32_16x16x32_bf16 v[28:31], v[76:79], v[218:221], v[28:31]
	v_mfma_f32_16x16x32_bf16 v[24:27], v[92:95], v[218:221], v[24:27]
	v_mfma_f32_16x16x32_bf16 v[12:15], v[76:79], v[226:229], v[12:15]
	v_mfma_f32_16x16x32_bf16 v[8:11], v[92:95], v[226:229], v[8:11]
	s_barrier
	s_add_u32 s38, s38, 0x80080
	s_addc_u32 s39, s39, 0
	s_add_i32 s52, s52, s60
	s_mov_b32 m0, s52
	s_nop 0
	global_load_lds_dwordx4 v152, s[38:39]
	s_add_i32 m0, s52, 0x2000
	s_nop 0
	global_load_lds_dwordx4 v162, s[38:39]
	s_add_i32 s30, s30, 2
	s_add_u32 s22, s22, 0x100
	s_addc_u32 s23, s23, 0
	s_add_u32 s17, s17, 0x100
	s_addc_u32 s21, s21, 0
	s_add_u32 s38, s22, 0xfff80080
	s_addc_u32 s39, s23, -1
	s_add_i32 s84, 0, 0x10000
	s_cmp_eq_u32 s30, 28
	s_cselect_b32 s53, s5, s39
	s_cselect_b32 s52, s6, s38
	s_cselect_b32 s39, s1, s21
	s_cselect_b32 s38, s7, s17
	s_add_i32 m0, s61, 0xc000
	s_cmp_gt_u32 s30, 29
	s_waitcnt vmcnt(6)
	s_barrier
	v_mfma_f32_16x16x32_bf16 v[52:55], v[230:233], v[144:147], v[52:55]
	v_mfma_f32_16x16x32_bf16 v[48:51], v[238:241], v[144:147], v[48:51]
	v_mfma_f32_16x16x32_bf16 v[36:39], v[230:233], v[188:191], v[36:39]
	v_mfma_f32_16x16x32_bf16 v[32:35], v[238:241], v[188:191], v[32:35]
	v_mfma_f32_16x16x32_bf16 v[20:23], v[230:233], v[214:217], v[20:23]
	v_mfma_f32_16x16x32_bf16 v[16:19], v[238:241], v[214:217], v[16:19]
	v_mfma_f32_16x16x32_bf16 v[4:7], v[230:233], v[222:225], v[4:7]
	v_mfma_f32_16x16x32_bf16 v[0:3], v[238:241], v[222:225], v[0:3]
	v_mfma_f32_16x16x32_bf16 v[52:55], v[234:237], v[148:151], v[52:55]
	v_mfma_f32_16x16x32_bf16 v[48:51], v[242:245], v[148:151], v[48:51]
	v_mfma_f32_16x16x32_bf16 v[36:39], v[234:237], v[210:213], v[36:39]
	v_mfma_f32_16x16x32_bf16 v[32:35], v[242:245], v[210:213], v[32:35]
	v_mfma_f32_16x16x32_bf16 v[20:23], v[234:237], v[218:221], v[20:23]
	v_mfma_f32_16x16x32_bf16 v[16:19], v[242:245], v[218:221], v[16:19]
	v_mfma_f32_16x16x32_bf16 v[4:7], v[234:237], v[226:229], v[4:7]
	v_mfma_f32_16x16x32_bf16 v[0:3], v[242:245], v[226:229], v[0:3]
	s_barrier
	s_cbranch_scc0 .LBB0_561
	s_cmpk_gt_u32 s15, 0xff
	s_cbranch_scc1 .Lal_e0_w
	s_barrier

.LBB0_773:
	ds_read_b128 v[144:147], v230
	ds_read_b128 v[148:151], v230 offset:1024
	ds_read_b128 v[162:165], v230 offset:2048
	ds_read_b128 v[166:169], v230 offset:3072
	ds_read_b128 v[170:173], v143
	ds_read_b128 v[174:177], v143 offset:1024
	ds_read_b128 v[178:181], v143 offset:2048
	ds_read_b128 v[182:185], v143 offset:3072
	ds_read_b128 v[186:189], v143 offset:4096
	ds_read_b128 v[190:193], v143 offset:5120
	ds_read_b128 v[206:209], v143 offset:6144
	ds_read_b128 v[210:213], v143 offset:7168
	global_load_lds_dwordx4 v134, s[20:21]
	s_add_i32 m0, s5, 0xe000
	s_nop 0
	global_load_lds_dwordx4 v136, s[20:21]
	s_waitcnt lgkmcnt(8)
	s_barrier
	s_waitcnt lgkmcnt(0)
	v_mfma_f32_16x16x32_bf16 v[124:127], v[144:147], v[170:173], v[124:127]
	v_mfma_f32_16x16x32_bf16 v[120:123], v[162:165], v[170:173], v[120:123]
	v_mfma_f32_16x16x32_bf16 v[108:111], v[144:147], v[178:181], v[108:111]
	v_mfma_f32_16x16x32_bf16 v[104:107], v[162:165], v[178:181], v[104:107]
	v_mfma_f32_16x16x32_bf16 v[92:95], v[144:147], v[186:189], v[92:95]
	v_mfma_f32_16x16x32_bf16 v[88:91], v[162:165], v[186:189], v[88:91]
	v_mfma_f32_16x16x32_bf16 v[76:79], v[144:147], v[206:209], v[76:79]
	v_mfma_f32_16x16x32_bf16 v[72:75], v[162:165], v[206:209], v[72:75]
	v_mfma_f32_16x16x32_bf16 v[124:127], v[148:151], v[174:177], v[124:127]
	v_mfma_f32_16x16x32_bf16 v[120:123], v[166:169], v[174:177], v[120:123]
	v_mfma_f32_16x16x32_bf16 v[108:111], v[148:151], v[182:185], v[108:111]
	v_mfma_f32_16x16x32_bf16 v[104:107], v[166:169], v[182:185], v[104:107]
	v_mfma_f32_16x16x32_bf16 v[92:95], v[148:151], v[190:193], v[92:95]
	v_mfma_f32_16x16x32_bf16 v[88:91], v[166:169], v[190:193], v[88:91]
	v_mfma_f32_16x16x32_bf16 v[76:79], v[148:151], v[210:213], v[76:79]
	v_mfma_f32_16x16x32_bf16 v[72:75], v[166:169], v[210:213], v[72:75]
	s_barrier
	s_add_i32 s68, 0, 0x14000
	s_add_i32 s61, s61, s4
	ds_read_b128 v[214:217], v231
	ds_read_b128 v[218:221], v231 offset:1024
	ds_read_b128 v[222:225], v231 offset:2048
	ds_read_b128 v[226:229], v231 offset:3072
	s_mov_b32 m0, s61
	s_nop 0
	global_load_lds_dwordx4 v152, s[22:23]
	s_add_i32 m0, s61, 0x2000
	s_nop 0
	global_load_lds_dwordx4 v132, s[22:23]
	s_waitcnt lgkmcnt(0)
	s_barrier
	v_mfma_f32_16x16x32_bf16 v[116:119], v[214:217], v[170:173], v[116:119]
	v_mfma_f32_16x16x32_bf16 v[112:115], v[222:225], v[170:173], v[112:115]
	v_mfma_f32_16x16x32_bf16 v[100:103], v[214:217], v[178:181], v[100:103]
	v_mfma_f32_16x16x32_bf16 v[96:99], v[222:225], v[178:181], v[96:99]
	v_mfma_f32_16x16x32_bf16 v[84:87], v[214:217], v[186:189], v[84:87]
	v_mfma_f32_16x16x32_bf16 v[80:83], v[222:225], v[186:189], v[80:83]
	v_mfma_f32_16x16x32_bf16 v[68:71], v[214:217], v[206:209], v[68:71]
	v_mfma_f32_16x16x32_bf16 v[64:67], v[222:225], v[206:209], v[64:67]
	v_mfma_f32_16x16x32_bf16 v[116:119], v[218:221], v[174:177], v[116:119]
	v_mfma_f32_16x16x32_bf16 v[112:115], v[226:229], v[174:177], v[112:115]
	v_mfma_f32_16x16x32_bf16 v[100:103], v[218:221], v[182:185], v[100:103]
	v_mfma_f32_16x16x32_bf16 v[96:99], v[226:229], v[182:185], v[96:99]
	v_mfma_f32_16x16x32_bf16 v[84:87], v[218:221], v[190:193], v[84:87]
	v_mfma_f32_16x16x32_bf16 v[80:83], v[226:229], v[190:193], v[80:83]
	v_mfma_f32_16x16x32_bf16 v[68:71], v[218:221], v[210:213], v[68:71]
	v_mfma_f32_16x16x32_bf16 v[64:67], v[226:229], v[210:213], v[64:67]
	s_barrier
	s_mov_b32 m0, s5
	s_add_u32 s98, s46, 0x80
	s_addc_u32 s99, s47, 0
	ds_read_b128 v[170:173], v143 offset:16384
	ds_read_b128 v[174:177], v143 offset:17408
	ds_read_b128 v[178:181], v143 offset:18432
	ds_read_b128 v[182:185], v143 offset:19456
	ds_read_b128 v[186:189], v143 offset:20480
	ds_read_b128 v[190:193], v143 offset:21504
	ds_read_b128 v[206:209], v143 offset:22528
	ds_read_b128 v[210:213], v143 offset:23552
	global_load_lds_dwordx4 v128, s[46:47]
	s_mov_b32 m0, s50
	s_nop 0
	global_load_lds_dwordx4 v130, s[46:47]
	s_waitcnt lgkmcnt(0)
	s_barrier
	v_mfma_f32_16x16x32_bf16 v[60:63], v[144:147], v[170:173], v[60:63]
	v_mfma_f32_16x16x32_bf16 v[56:59], v[162:165], v[170:173], v[56:59]
	v_mfma_f32_16x16x32_bf16 v[44:47], v[144:147], v[178:181], v[44:47]
	v_mfma_f32_16x16x32_bf16 v[40:43], v[162:165], v[178:181], v[40:43]
	v_mfma_f32_16x16x32_bf16 v[28:31], v[144:147], v[186:189], v[28:31]
	v_mfma_f32_16x16x32_bf16 v[24:27], v[162:165], v[186:189], v[24:27]
	v_mfma_f32_16x16x32_bf16 v[12:15], v[144:147], v[206:209], v[12:15]
	v_mfma_f32_16x16x32_bf16 v[8:11], v[162:165], v[206:209], v[8:11]
	v_mfma_f32_16x16x32_bf16 v[60:63], v[148:151], v[174:177], v[60:63]
	v_mfma_f32_16x16x32_bf16 v[56:59], v[166:169], v[174:177], v[56:59]
	v_mfma_f32_16x16x32_bf16 v[44:47], v[148:151], v[182:185], v[44:47]
	v_mfma_f32_16x16x32_bf16 v[40:43], v[166:169], v[182:185], v[40:43]
	v_mfma_f32_16x16x32_bf16 v[28:31], v[148:151], v[190:193], v[28:31]
	v_mfma_f32_16x16x32_bf16 v[24:27], v[166:169], v[190:193], v[24:27]
	v_mfma_f32_16x16x32_bf16 v[12:15], v[148:151], v[210:213], v[12:15]
	v_mfma_f32_16x16x32_bf16 v[8:11], v[166:169], v[210:213], v[8:11]
	s_barrier
	s_add_u32 s62, s22, 0x80000
	s_addc_u32 s63, s23, 0
	s_add_i32 s61, s68, s4
	s_mov_b32 m0, s61
	s_nop 0
	global_load_lds_dwordx4 v152, s[62:63]
	s_add_i32 m0, s61, 0x2000
	s_nop 0
	global_load_lds_dwordx4 v132, s[62:63]
	s_add_i32 s61, 0, 0x18000
	s_add_u32 s46, s46, 0x80000
	s_addc_u32 s47, s47, 0
	s_mov_b32 m0, s51
	s_waitcnt vmcnt(6)
	s_barrier
	v_mfma_f32_16x16x32_bf16 v[52:55], v[214:217], v[170:173], v[52:55]
	v_mfma_f32_16x16x32_bf16 v[48:51], v[222:225], v[170:173], v[48:51]
	v_mfma_f32_16x16x32_bf16 v[36:39], v[214:217], v[178:181], v[36:39]
	v_mfma_f32_16x16x32_bf16 v[32:35], v[222:225], v[178:181], v[32:35]
	v_mfma_f32_16x16x32_bf16 v[20:23], v[214:217], v[186:189], v[20:23]
	v_mfma_f32_16x16x32_bf16 v[16:19], v[222:225], v[186:189], v[16:19]
	v_mfma_f32_16x16x32_bf16 v[4:7], v[214:217], v[206:209], v[4:7]
	v_mfma_f32_16x16x32_bf16 v[0:3], v[222:225], v[206:209], v[0:3]
	v_mfma_f32_16x16x32_bf16 v[52:55], v[218:221], v[174:177], v[52:55]
	v_mfma_f32_16x16x32_bf16 v[48:51], v[226:229], v[174:177], v[48:51]
	v_mfma_f32_16x16x32_bf16 v[36:39], v[218:221], v[182:185], v[36:39]
	v_mfma_f32_16x16x32_bf16 v[32:35], v[226:229], v[182:185], v[32:35]
	v_mfma_f32_16x16x32_bf16 v[20:23], v[218:221], v[190:193], v[20:23]
	v_mfma_f32_16x16x32_bf16 v[16:19], v[226:229], v[190:193], v[16:19]
	v_mfma_f32_16x16x32_bf16 v[4:7], v[218:221], v[210:213], v[4:7]
	v_mfma_f32_16x16x32_bf16 v[0:3], v[226:229], v[210:213], v[0:3]
	s_barrier
	ds_read_b128 v[144:147], v232
	ds_read_b128 v[148:151], v232 offset:1024
	ds_read_b128 v[162:165], v232 offset:2048
	ds_read_b128 v[166:169], v232 offset:3072
	ds_read_b128 v[170:173], v143 offset:32768
	ds_read_b128 v[174:177], v143 offset:33792
	ds_read_b128 v[178:181], v143 offset:34816
	ds_read_b128 v[182:185], v143 offset:35840
	ds_read_b128 v[186:189], v143 offset:36864
	ds_read_b128 v[190:193], v143 offset:37888
	ds_read_b128 v[206:209], v143 offset:38912
	ds_read_b128 v[210:213], v143 offset:39936
	global_load_lds_dwordx4 v128, s[46:47]
	s_mov_b32 m0, s52
	s_nop 0
	global_load_lds_dwordx4 v130, s[46:47]
	s_waitcnt lgkmcnt(8)
	s_barrier
	s_waitcnt lgkmcnt(0)
	v_mfma_f32_16x16x32_bf16 v[124:127], v[144:147], v[170:173], v[124:127]
	v_mfma_f32_16x16x32_bf16 v[120:123], v[162:165], v[170:173], v[120:123]
	v_mfma_f32_16x16x32_bf16 v[108:111], v[144:147], v[178:181], v[108:111]
	v_mfma_f32_16x16x32_bf16 v[104:107], v[162:165], v[178:181], v[104:107]
	v_mfma_f32_16x16x32_bf16 v[92:95], v[144:147], v[186:189], v[92:95]
	v_mfma_f32_16x16x32_bf16 v[88:91], v[162:165], v[186:189], v[88:91]
	v_mfma_f32_16x16x32_bf16 v[76:79], v[144:147], v[206:209], v[76:79]
	v_mfma_f32_16x16x32_bf16 v[72:75], v[162:165], v[206:209], v[72:75]
	v_mfma_f32_16x16x32_bf16 v[124:127], v[148:151], v[174:177], v[124:127]
	v_mfma_f32_16x16x32_bf16 v[120:123], v[166:169], v[174:177], v[120:123]
	v_mfma_f32_16x16x32_bf16 v[108:111], v[148:151], v[182:185], v[108:111]
	v_mfma_f32_16x16x32_bf16 v[104:107], v[166:169], v[182:185], v[104:107]
	v_mfma_f32_16x16x32_bf16 v[92:95], v[148:151], v[190:193], v[92:95]
	v_mfma_f32_16x16x32_bf16 v[88:91], v[166:169], v[190:193], v[88:91]
	v_mfma_f32_16x16x32_bf16 v[76:79], v[148:151], v[210:213], v[76:79]
	v_mfma_f32_16x16x32_bf16 v[72:75], v[166:169], v[210:213], v[72:75]
	s_barrier
	s_add_i32 s46, 0, 0x1c000
	s_add_i32 s47, s61, s4
	s_add_u32 s100, s22, 0x80
	s_addc_u32 s101, s23, 0
	s_mov_b32 m0, s47
	ds_read_b128 v[214:217], v233
	ds_read_b128 v[218:221], v233 offset:1024
	ds_read_b128 v[222:225], v233 offset:2048
	ds_read_b128 v[226:229], v233 offset:3072
	global_load_lds_dwordx4 v152, s[100:101]
	s_add_i32 m0, s47, 0x2000
	s_nop 0
	global_load_lds_dwordx4 v132, s[100:101]
	s_waitcnt lgkmcnt(0)
	s_barrier
	v_mfma_f32_16x16x32_bf16 v[116:119], v[214:217], v[170:173], v[116:119]
	v_mfma_f32_16x16x32_bf16 v[112:115], v[222:225], v[170:173], v[112:115]
	v_mfma_f32_16x16x32_bf16 v[100:103], v[214:217], v[178:181], v[100:103]
	v_mfma_f32_16x16x32_bf16 v[96:99], v[222:225], v[178:181], v[96:99]
	v_mfma_f32_16x16x32_bf16 v[84:87], v[214:217], v[186:189], v[84:87]
	v_mfma_f32_16x16x32_bf16 v[80:83], v[222:225], v[186:189], v[80:83]
	v_mfma_f32_16x16x32_bf16 v[68:71], v[214:217], v[206:209], v[68:71]
	v_mfma_f32_16x16x32_bf16 v[64:67], v[222:225], v[206:209], v[64:67]
	v_mfma_f32_16x16x32_bf16 v[116:119], v[218:221], v[174:177], v[116:119]
	v_mfma_f32_16x16x32_bf16 v[112:115], v[226:229], v[174:177], v[112:115]
	v_mfma_f32_16x16x32_bf16 v[100:103], v[218:221], v[182:185], v[100:103]
	v_mfma_f32_16x16x32_bf16 v[96:99], v[226:229], v[182:185], v[96:99]
	v_mfma_f32_16x16x32_bf16 v[84:87], v[218:221], v[190:193], v[84:87]
	v_mfma_f32_16x16x32_bf16 v[80:83], v[226:229], v[190:193], v[80:83]
	v_mfma_f32_16x16x32_bf16 v[68:71], v[218:221], v[210:213], v[68:71]
	v_mfma_f32_16x16x32_bf16 v[64:67], v[226:229], v[210:213], v[64:67]
	s_barrier
	s_mov_b32 m0, s53
	ds_read_b128 v[170:173], v143 offset:49152
	ds_read_b128 v[174:177], v143 offset:50176
	ds_read_b128 v[178:181], v143 offset:51200
	ds_read_b128 v[182:185], v143 offset:52224
	ds_read_b128 v[186:189], v143 offset:53248
	ds_read_b128 v[190:193], v143 offset:54272
	ds_read_b128 v[206:209], v143 offset:55296
	ds_read_b128 v[210:213], v143 offset:56320
	global_load_lds_dwordx4 v128, s[98:99]
	s_mov_b32 m0, s54
	s_nop 0
	global_load_lds_dwordx4 v130, s[98:99]
	s_waitcnt lgkmcnt(0)
	s_barrier
	v_mfma_f32_16x16x32_bf16 v[60:63], v[144:147], v[170:173], v[60:63]
	v_mfma_f32_16x16x32_bf16 v[56:59], v[162:165], v[170:173], v[56:59]
	v_mfma_f32_16x16x32_bf16 v[44:47], v[144:147], v[178:181], v[44:47]
	v_mfma_f32_16x16x32_bf16 v[40:43], v[162:165], v[178:181], v[40:43]
	v_mfma_f32_16x16x32_bf16 v[28:31], v[144:147], v[186:189], v[28:31]
	v_mfma_f32_16x16x32_bf16 v[24:27], v[162:165], v[186:189], v[24:27]
	v_mfma_f32_16x16x32_bf16 v[12:15], v[144:147], v[206:209], v[12:15]
	v_mfma_f32_16x16x32_bf16 v[8:11], v[162:165], v[206:209], v[8:11]
	v_mfma_f32_16x16x32_bf16 v[60:63], v[148:151], v[174:177], v[60:63]
	v_mfma_f32_16x16x32_bf16 v[56:59], v[166:169], v[174:177], v[56:59]
	v_mfma_f32_16x16x32_bf16 v[44:47], v[148:151], v[182:185], v[44:47]
	v_mfma_f32_16x16x32_bf16 v[40:43], v[166:169], v[182:185], v[40:43]
	v_mfma_f32_16x16x32_bf16 v[28:31], v[148:151], v[190:193], v[28:31]
	v_mfma_f32_16x16x32_bf16 v[24:27], v[166:169], v[190:193], v[24:27]
	v_mfma_f32_16x16x32_bf16 v[12:15], v[148:151], v[210:213], v[12:15]
	v_mfma_f32_16x16x32_bf16 v[8:11], v[166:169], v[210:213], v[8:11]
	s_barrier
	s_add_u32 s22, s22, 0x80080
	s_addc_u32 s23, s23, 0
	s_add_i32 s46, s46, s4
	s_mov_b32 m0, s46
	s_nop 0
	global_load_lds_dwordx4 v152, s[22:23]
	s_add_i32 m0, s46, 0x2000
	s_nop 0
	global_load_lds_dwordx4 v132, s[22:23]
	s_add_i32 s60, s60, 2
	s_add_u32 s20, s20, 0x100
	s_addc_u32 s21, s21, 0
	s_add_u32 s58, s58, 0x100
	s_addc_u32 s59, s59, 0
	s_add_u32 s22, s20, 0xfff80080
	s_addc_u32 s23, s21, -1
	s_add_i32 s61, 0, 0x10000
	s_cmp_eq_u32 s60, 28
	s_cselect_b32 s47, s35, s23
	s_cselect_b32 s46, s56, s22
	s_cselect_b32 s23, s25, s59
	s_cselect_b32 s22, s57, s58
	s_add_i32 m0, s5, 0xc000
	s_cmp_gt_u32 s60, 29
	s_waitcnt vmcnt(6)
	s_barrier
	v_mfma_f32_16x16x32_bf16 v[52:55], v[214:217], v[170:173], v[52:55]
	v_mfma_f32_16x16x32_bf16 v[48:51], v[222:225], v[170:173], v[48:51]
	v_mfma_f32_16x16x32_bf16 v[36:39], v[214:217], v[178:181], v[36:39]
	v_mfma_f32_16x16x32_bf16 v[32:35], v[222:225], v[178:181], v[32:35]
	v_mfma_f32_16x16x32_bf16 v[20:23], v[214:217], v[186:189], v[20:23]
	v_mfma_f32_16x16x32_bf16 v[16:19], v[222:225], v[186:189], v[16:19]
	v_mfma_f32_16x16x32_bf16 v[4:7], v[214:217], v[206:209], v[4:7]
	v_mfma_f32_16x16x32_bf16 v[0:3], v[222:225], v[206:209], v[0:3]
	v_mfma_f32_16x16x32_bf16 v[52:55], v[218:221], v[174:177], v[52:55]
	v_mfma_f32_16x16x32_bf16 v[48:51], v[226:229], v[174:177], v[48:51]
	v_mfma_f32_16x16x32_bf16 v[36:39], v[218:221], v[182:185], v[36:39]
	v_mfma_f32_16x16x32_bf16 v[32:35], v[226:229], v[182:185], v[32:35]
	v_mfma_f32_16x16x32_bf16 v[20:23], v[218:221], v[190:193], v[20:23]
	v_mfma_f32_16x16x32_bf16 v[16:19], v[226:229], v[190:193], v[16:19]
	v_mfma_f32_16x16x32_bf16 v[4:7], v[218:221], v[210:213], v[4:7]
	v_mfma_f32_16x16x32_bf16 v[0:3], v[226:229], v[210:213], v[0:3]
	s_barrier
	s_cbranch_scc0 .LBB0_773
	s_cmpk_gt_u32 s14, 0xff
	s_cbranch_scc1 .Lal_e0_m
	s_barrier

.LBB0_836:
	ds_read_b128 v[120:123], v248
	ds_read_b128 v[124:127], v248 offset:1024
	ds_read_b128 v[132:135], v248 offset:2048
	ds_read_b128 v[136:139], v248 offset:3072
	ds_read_b128 v[186:189], v185
	ds_read_b128 v[190:193], v185 offset:1024
	ds_read_b128 v[206:209], v185 offset:2048
	ds_read_b128 v[210:213], v185 offset:3072
	ds_read_b128 v[214:217], v185 offset:4096
	ds_read_b128 v[218:221], v185 offset:5120
	ds_read_b128 v[222:225], v185 offset:6144
	ds_read_b128 v[226:229], v185 offset:7168
	global_load_lds_dwordx4 v176, s[20:21]
	s_add_i32 m0, s52, 0xe000
	s_nop 0
	global_load_lds_dwordx4 v178, s[20:21]
	s_waitcnt lgkmcnt(8)
	s_barrier
	s_waitcnt lgkmcnt(0)
	v_mfma_f32_16x16x32_bf16 v[140:143], v[120:123], v[186:189], v[140:143]
	v_mfma_f32_16x16x32_bf16 v[128:131], v[132:135], v[186:189], v[128:131]
	v_mfma_f32_16x16x32_bf16 v[112:115], v[120:123], v[206:209], v[112:115]
	v_mfma_f32_16x16x32_bf16 v[104:107], v[132:135], v[206:209], v[104:107]
	v_mfma_f32_16x16x32_bf16 v[96:99], v[120:123], v[214:217], v[96:99]
	v_mfma_f32_16x16x32_bf16 v[88:91], v[132:135], v[214:217], v[88:91]
	v_mfma_f32_16x16x32_bf16 v[80:83], v[120:123], v[222:225], v[80:83]
	v_mfma_f32_16x16x32_bf16 v[72:75], v[132:135], v[222:225], v[72:75]
	v_mfma_f32_16x16x32_bf16 v[140:143], v[124:127], v[190:193], v[140:143]
	v_mfma_f32_16x16x32_bf16 v[128:131], v[136:139], v[190:193], v[128:131]
	v_mfma_f32_16x16x32_bf16 v[112:115], v[124:127], v[210:213], v[112:115]
	v_mfma_f32_16x16x32_bf16 v[104:107], v[136:139], v[210:213], v[104:107]
	v_mfma_f32_16x16x32_bf16 v[96:99], v[124:127], v[218:221], v[96:99]
	v_mfma_f32_16x16x32_bf16 v[88:91], v[136:139], v[218:221], v[88:91]
	v_mfma_f32_16x16x32_bf16 v[80:83], v[124:127], v[226:229], v[80:83]
	v_mfma_f32_16x16x32_bf16 v[72:75], v[136:139], v[226:229], v[72:75]
	s_barrier
	s_add_i32 s80, 0, 0x14000
	s_add_i32 s78, s78, s51
	ds_read_b128 v[230:233], v249
	ds_read_b128 v[234:237], v249 offset:1024
	ds_read_b128 v[238:241], v249 offset:2048
	ds_read_b128 v[242:245], v249 offset:3072
	s_mov_b32 m0, s78
	s_nop 0
	global_load_lds_dwordx4 v152, s[22:23]
	s_add_i32 m0, s78, 0x2000
	s_nop 0
	global_load_lds_dwordx4 v144, s[22:23]
	s_waitcnt lgkmcnt(0)
	s_barrier
	v_mfma_f32_16x16x32_bf16 v[116:119], v[230:233], v[186:189], v[116:119]
	v_mfma_f32_16x16x32_bf16 v[108:111], v[238:241], v[186:189], v[108:111]
	v_mfma_f32_16x16x32_bf16 v[100:103], v[230:233], v[206:209], v[100:103]
	v_mfma_f32_16x16x32_bf16 v[92:95], v[238:241], v[206:209], v[92:95]
	v_mfma_f32_16x16x32_bf16 v[84:87], v[230:233], v[214:217], v[84:87]
	v_mfma_f32_16x16x32_bf16 v[76:79], v[238:241], v[214:217], v[76:79]
	v_mfma_f32_16x16x32_bf16 v[68:71], v[230:233], v[222:225], v[68:71]
	v_mfma_f32_16x16x32_bf16 v[64:67], v[238:241], v[222:225], v[64:67]
	v_mfma_f32_16x16x32_bf16 v[116:119], v[234:237], v[190:193], v[116:119]
	v_mfma_f32_16x16x32_bf16 v[108:111], v[242:245], v[190:193], v[108:111]
	v_mfma_f32_16x16x32_bf16 v[100:103], v[234:237], v[210:213], v[100:103]
	v_mfma_f32_16x16x32_bf16 v[92:95], v[242:245], v[210:213], v[92:95]
	v_mfma_f32_16x16x32_bf16 v[84:87], v[234:237], v[218:221], v[84:87]
	v_mfma_f32_16x16x32_bf16 v[76:79], v[242:245], v[218:221], v[76:79]
	v_mfma_f32_16x16x32_bf16 v[68:71], v[234:237], v[226:229], v[68:71]
	v_mfma_f32_16x16x32_bf16 v[64:67], v[242:245], v[226:229], v[64:67]
	s_barrier
	s_mov_b32 m0, s52
	s_add_u32 s98, s34, 0x80
	s_addc_u32 s99, s35, 0
	ds_read_b128 v[186:189], v185 offset:16384
	ds_read_b128 v[190:193], v185 offset:17408
	ds_read_b128 v[206:209], v185 offset:18432
	ds_read_b128 v[210:213], v185 offset:19456
	ds_read_b128 v[214:217], v185 offset:20480
	ds_read_b128 v[218:221], v185 offset:21504
	ds_read_b128 v[222:225], v185 offset:22528
	ds_read_b128 v[226:229], v185 offset:23552
	global_load_lds_dwordx4 v148, s[34:35]
	s_mov_b32 m0, s53
	s_nop 0
	global_load_lds_dwordx4 v146, s[34:35]
	s_waitcnt lgkmcnt(0)
	s_barrier
	v_mfma_f32_16x16x32_bf16 v[60:63], v[120:123], v[186:189], v[60:63]
	v_mfma_f32_16x16x32_bf16 v[56:59], v[132:135], v[186:189], v[56:59]
	v_mfma_f32_16x16x32_bf16 v[48:51], v[120:123], v[206:209], v[48:51]
	v_mfma_f32_16x16x32_bf16 v[40:43], v[132:135], v[206:209], v[40:43]
	v_mfma_f32_16x16x32_bf16 v[32:35], v[120:123], v[214:217], v[32:35]
	v_mfma_f32_16x16x32_bf16 v[24:27], v[132:135], v[214:217], v[24:27]
	v_mfma_f32_16x16x32_bf16 v[16:19], v[120:123], v[222:225], v[16:19]
	v_mfma_f32_16x16x32_bf16 v[8:11], v[132:135], v[222:225], v[8:11]
	v_mfma_f32_16x16x32_bf16 v[60:63], v[124:127], v[190:193], v[60:63]
	v_mfma_f32_16x16x32_bf16 v[56:59], v[136:139], v[190:193], v[56:59]
	v_mfma_f32_16x16x32_bf16 v[48:51], v[124:127], v[210:213], v[48:51]
	v_mfma_f32_16x16x32_bf16 v[40:43], v[136:139], v[210:213], v[40:43]
	v_mfma_f32_16x16x32_bf16 v[32:35], v[124:127], v[218:221], v[32:35]
	v_mfma_f32_16x16x32_bf16 v[24:27], v[136:139], v[218:221], v[24:27]
	v_mfma_f32_16x16x32_bf16 v[16:19], v[124:127], v[226:229], v[16:19]
	v_mfma_f32_16x16x32_bf16 v[8:11], v[136:139], v[226:229], v[8:11]
	s_barrier
	s_add_u32 s78, s22, 0x200000
	s_addc_u32 s79, s23, 0
	s_add_i32 s80, s80, s51
	s_mov_b32 m0, s80
	s_nop 0
	global_load_lds_dwordx4 v152, s[78:79]
	s_add_i32 m0, s80, 0x2000
	s_nop 0
	global_load_lds_dwordx4 v144, s[78:79]
	s_add_i32 s78, 0, 0x18000
	s_add_u32 s34, s34, 0x200000
	s_addc_u32 s35, s35, 0
	s_mov_b32 m0, s54
	s_waitcnt vmcnt(6)
	s_barrier
	v_mfma_f32_16x16x32_bf16 v[52:55], v[230:233], v[186:189], v[52:55]
	v_mfma_f32_16x16x32_bf16 v[44:47], v[238:241], v[186:189], v[44:47]
	v_mfma_f32_16x16x32_bf16 v[36:39], v[230:233], v[206:209], v[36:39]
	v_mfma_f32_16x16x32_bf16 v[28:31], v[238:241], v[206:209], v[28:31]
	v_mfma_f32_16x16x32_bf16 v[20:23], v[230:233], v[214:217], v[20:23]
	v_mfma_f32_16x16x32_bf16 v[12:15], v[238:241], v[214:217], v[12:15]
	v_mfma_f32_16x16x32_bf16 v[4:7], v[230:233], v[222:225], v[4:7]
	v_mfma_f32_16x16x32_bf16 v[0:3], v[238:241], v[222:225], v[0:3]
	v_mfma_f32_16x16x32_bf16 v[52:55], v[234:237], v[190:193], v[52:55]
	v_mfma_f32_16x16x32_bf16 v[44:47], v[242:245], v[190:193], v[44:47]
	v_mfma_f32_16x16x32_bf16 v[36:39], v[234:237], v[210:213], v[36:39]
	v_mfma_f32_16x16x32_bf16 v[28:31], v[242:245], v[210:213], v[28:31]
	v_mfma_f32_16x16x32_bf16 v[20:23], v[234:237], v[218:221], v[20:23]
	v_mfma_f32_16x16x32_bf16 v[12:15], v[242:245], v[218:221], v[12:15]
	v_mfma_f32_16x16x32_bf16 v[4:7], v[234:237], v[226:229], v[4:7]
	v_mfma_f32_16x16x32_bf16 v[0:3], v[242:245], v[226:229], v[0:3]
	s_barrier
	ds_read_b128 v[120:123], v250
	ds_read_b128 v[124:127], v250 offset:1024
	ds_read_b128 v[132:135], v250 offset:2048
	ds_read_b128 v[136:139], v250 offset:3072
	ds_read_b128 v[186:189], v185 offset:32768
	ds_read_b128 v[190:193], v185 offset:33792
	ds_read_b128 v[206:209], v185 offset:34816
	ds_read_b128 v[210:213], v185 offset:35840
	ds_read_b128 v[214:217], v185 offset:36864
	ds_read_b128 v[218:221], v185 offset:37888
	ds_read_b128 v[222:225], v185 offset:38912
	ds_read_b128 v[226:229], v185 offset:39936
	global_load_lds_dwordx4 v148, s[34:35]
	s_mov_b32 m0, s55
	s_nop 0
	global_load_lds_dwordx4 v146, s[34:35]
	s_waitcnt lgkmcnt(8)
	s_barrier
	s_waitcnt lgkmcnt(0)
	v_mfma_f32_16x16x32_bf16 v[140:143], v[120:123], v[186:189], v[140:143]
	v_mfma_f32_16x16x32_bf16 v[128:131], v[132:135], v[186:189], v[128:131]
	v_mfma_f32_16x16x32_bf16 v[112:115], v[120:123], v[206:209], v[112:115]
	v_mfma_f32_16x16x32_bf16 v[104:107], v[132:135], v[206:209], v[104:107]
	v_mfma_f32_16x16x32_bf16 v[96:99], v[120:123], v[214:217], v[96:99]
	v_mfma_f32_16x16x32_bf16 v[88:91], v[132:135], v[214:217], v[88:91]
	v_mfma_f32_16x16x32_bf16 v[80:83], v[120:123], v[222:225], v[80:83]
	v_mfma_f32_16x16x32_bf16 v[72:75], v[132:135], v[222:225], v[72:75]
	v_mfma_f32_16x16x32_bf16 v[140:143], v[124:127], v[190:193], v[140:143]
	v_mfma_f32_16x16x32_bf16 v[128:131], v[136:139], v[190:193], v[128:131]
	v_mfma_f32_16x16x32_bf16 v[112:115], v[124:127], v[210:213], v[112:115]
	v_mfma_f32_16x16x32_bf16 v[104:107], v[136:139], v[210:213], v[104:107]
	v_mfma_f32_16x16x32_bf16 v[96:99], v[124:127], v[218:221], v[96:99]
	v_mfma_f32_16x16x32_bf16 v[88:91], v[136:139], v[218:221], v[88:91]
	v_mfma_f32_16x16x32_bf16 v[80:83], v[124:127], v[226:229], v[80:83]
	v_mfma_f32_16x16x32_bf16 v[72:75], v[136:139], v[226:229], v[72:75]
	s_barrier
	s_add_i32 s34, 0, 0x1c000
	s_add_i32 s35, s78, s51
	s_add_u32 s100, s22, 0x80
	s_addc_u32 s101, s23, 0
	s_mov_b32 m0, s35
	ds_read_b128 v[230:233], v251
	ds_read_b128 v[234:237], v251 offset:1024
	ds_read_b128 v[238:241], v251 offset:2048
	ds_read_b128 v[242:245], v251 offset:3072
	global_load_lds_dwordx4 v152, s[100:101]
	s_add_i32 m0, s35, 0x2000
	s_nop 0
	global_load_lds_dwordx4 v144, s[100:101]
	s_waitcnt lgkmcnt(0)
	s_barrier
	v_mfma_f32_16x16x32_bf16 v[116:119], v[230:233], v[186:189], v[116:119]
	v_mfma_f32_16x16x32_bf16 v[108:111], v[238:241], v[186:189], v[108:111]
	v_mfma_f32_16x16x32_bf16 v[100:103], v[230:233], v[206:209], v[100:103]
	v_mfma_f32_16x16x32_bf16 v[92:95], v[238:241], v[206:209], v[92:95]
	v_mfma_f32_16x16x32_bf16 v[84:87], v[230:233], v[214:217], v[84:87]
	v_mfma_f32_16x16x32_bf16 v[76:79], v[238:241], v[214:217], v[76:79]
	v_mfma_f32_16x16x32_bf16 v[68:71], v[230:233], v[222:225], v[68:71]
	v_mfma_f32_16x16x32_bf16 v[64:67], v[238:241], v[222:225], v[64:67]
	v_mfma_f32_16x16x32_bf16 v[116:119], v[234:237], v[190:193], v[116:119]
	v_mfma_f32_16x16x32_bf16 v[108:111], v[242:245], v[190:193], v[108:111]
	v_mfma_f32_16x16x32_bf16 v[100:103], v[234:237], v[210:213], v[100:103]
	v_mfma_f32_16x16x32_bf16 v[92:95], v[242:245], v[210:213], v[92:95]
	v_mfma_f32_16x16x32_bf16 v[84:87], v[234:237], v[218:221], v[84:87]
	v_mfma_f32_16x16x32_bf16 v[76:79], v[242:245], v[218:221], v[76:79]
	v_mfma_f32_16x16x32_bf16 v[68:71], v[234:237], v[226:229], v[68:71]
	v_mfma_f32_16x16x32_bf16 v[64:67], v[242:245], v[226:229], v[64:67]
	s_barrier
	s_mov_b32 m0, s60
	ds_read_b128 v[186:189], v185 offset:49152
	ds_read_b128 v[190:193], v185 offset:50176
	ds_read_b128 v[206:209], v185 offset:51200
	ds_read_b128 v[210:213], v185 offset:52224
	ds_read_b128 v[214:217], v185 offset:53248
	ds_read_b128 v[218:221], v185 offset:54272
	ds_read_b128 v[222:225], v185 offset:55296
	ds_read_b128 v[226:229], v185 offset:56320
	global_load_lds_dwordx4 v148, s[98:99]
	s_mov_b32 m0, s61
	s_nop 0
	global_load_lds_dwordx4 v146, s[98:99]
	s_waitcnt lgkmcnt(0)
	s_barrier
	v_mfma_f32_16x16x32_bf16 v[60:63], v[120:123], v[186:189], v[60:63]
	v_mfma_f32_16x16x32_bf16 v[56:59], v[132:135], v[186:189], v[56:59]
	v_mfma_f32_16x16x32_bf16 v[48:51], v[120:123], v[206:209], v[48:51]
	v_mfma_f32_16x16x32_bf16 v[40:43], v[132:135], v[206:209], v[40:43]
	v_mfma_f32_16x16x32_bf16 v[32:35], v[120:123], v[214:217], v[32:35]
	v_mfma_f32_16x16x32_bf16 v[24:27], v[132:135], v[214:217], v[24:27]
	v_mfma_f32_16x16x32_bf16 v[16:19], v[120:123], v[222:225], v[16:19]
	v_mfma_f32_16x16x32_bf16 v[8:11], v[132:135], v[222:225], v[8:11]
	v_mfma_f32_16x16x32_bf16 v[60:63], v[124:127], v[190:193], v[60:63]
	v_mfma_f32_16x16x32_bf16 v[56:59], v[136:139], v[190:193], v[56:59]
	v_mfma_f32_16x16x32_bf16 v[48:51], v[124:127], v[210:213], v[48:51]
	v_mfma_f32_16x16x32_bf16 v[40:43], v[136:139], v[210:213], v[40:43]
	v_mfma_f32_16x16x32_bf16 v[32:35], v[124:127], v[218:221], v[32:35]
	v_mfma_f32_16x16x32_bf16 v[24:27], v[136:139], v[218:221], v[24:27]
	v_mfma_f32_16x16x32_bf16 v[16:19], v[124:127], v[226:229], v[16:19]
	v_mfma_f32_16x16x32_bf16 v[8:11], v[136:139], v[226:229], v[8:11]
	s_barrier
	s_add_u32 s22, s22, 0x200080
	s_addc_u32 s23, s23, 0
	s_add_i32 s34, s34, s51
	s_mov_b32 m0, s34
	s_nop 0
	global_load_lds_dwordx4 v152, s[22:23]
	s_add_i32 m0, s34, 0x2000
	s_nop 0
	global_load_lds_dwordx4 v144, s[22:23]
	s_add_i32 s69, s69, 2
	s_add_u32 s20, s20, 0x100
	s_addc_u32 s21, s21, 0
	s_add_u32 s63, s63, 0x100
	s_addc_u32 s68, s68, 0
	s_add_u32 s22, s20, 0xffe00080
	s_addc_u32 s23, s21, -1
	s_add_i32 s78, 0, 0x10000
	s_cmpk_eq_i32 s69, 0x7c
	s_cselect_b32 s35, s6, s23
	s_cselect_b32 s34, s7, s22
	s_cselect_b32 s23, s1, s68
	s_cselect_b32 s22, s17, s63
	s_add_i32 m0, s52, 0xc000
	s_cmpk_gt_u32 s69, 0x7d
	s_waitcnt vmcnt(6)
	s_barrier
	v_mfma_f32_16x16x32_bf16 v[52:55], v[230:233], v[186:189], v[52:55]
	v_mfma_f32_16x16x32_bf16 v[44:47], v[238:241], v[186:189], v[44:47]
	v_mfma_f32_16x16x32_bf16 v[36:39], v[230:233], v[206:209], v[36:39]
	v_mfma_f32_16x16x32_bf16 v[28:31], v[238:241], v[206:209], v[28:31]
	v_mfma_f32_16x16x32_bf16 v[20:23], v[230:233], v[214:217], v[20:23]
	v_mfma_f32_16x16x32_bf16 v[12:15], v[238:241], v[214:217], v[12:15]
	v_mfma_f32_16x16x32_bf16 v[4:7], v[230:233], v[222:225], v[4:7]
	v_mfma_f32_16x16x32_bf16 v[0:3], v[238:241], v[222:225], v[0:3]
	v_mfma_f32_16x16x32_bf16 v[52:55], v[234:237], v[190:193], v[52:55]
	v_mfma_f32_16x16x32_bf16 v[44:47], v[242:245], v[190:193], v[44:47]
	v_mfma_f32_16x16x32_bf16 v[36:39], v[234:237], v[210:213], v[36:39]
	v_mfma_f32_16x16x32_bf16 v[28:31], v[242:245], v[210:213], v[28:31]
	v_mfma_f32_16x16x32_bf16 v[20:23], v[234:237], v[218:221], v[20:23]
	v_mfma_f32_16x16x32_bf16 v[12:15], v[242:245], v[218:221], v[12:15]
	v_mfma_f32_16x16x32_bf16 v[4:7], v[234:237], v[226:229], v[4:7]
	v_mfma_f32_16x16x32_bf16 v[0:3], v[242:245], v[226:229], v[0:3]
	s_barrier
	s_cbranch_scc0 .LBB0_836
	s_cmpk_gt_u32 s42, 0xff
	s_cbranch_scc1 .Lal_e0_q
	s_barrier
